# P1 in-proj epilogue: all 8 rstd loads hoisted, counted waits keep stores in flight
# speedup vs baseline: 1.0553x; 1.0015x over previous
.LBB0_109:
	v_or_b32_e32 v130, s24, v146
	v_add_u32_e32 v136, s25, v130
	v_or_b32_e32 v140, 16, v136
	v_ashrrev_i32_e32 v137, 31, v136
	v_ashrrev_i32_e32 v141, 31, v140
	v_lshl_add_u64 v[138:139], v[136:137], 2, s[2:3]
	v_lshl_add_u64 v[132:133], v[140:141], 2, s[2:3]
	global_load_dword v130, v[138:139], off
	global_load_dword v137, v[132:133], off
	global_load_dword v150, v[138:139], off offset:128
	global_load_dword v151, v[138:139], off offset:192
	global_load_dword v152, v[138:139], off offset:512
	global_load_dword v153, v[138:139], off offset:576
	global_load_dword v154, v[138:139], off offset:640
	global_load_dword v155, v[138:139], off offset:704
	v_or_b32_e32 v134, s22, v145
	v_or_b32_e32 v134, s23, v134
	v_mov_b64_e32 v[132:133], s[60:61]
	v_ashrrev_i32_e32 v135, 31, v134
	v_mad_i64_i32 v[142:143], s[22:23], v136, s36, v[132:133]
	v_lshlrev_b64 v[134:135], 1, v[134:135]
	v_mad_i64_i32 v[140:141], s[22:23], v140, s36, v[132:133]
	v_lshl_add_u64 v[142:143], v[142:143], 0, v[134:135]
	v_lshl_add_u64 v[140:141], v[140:141], 0, v[134:135]
	s_add_i32 s37, s37, s58
	s_cmpk_gt_i32 s37, 0x4a3
	s_waitcnt vmcnt(6)
	v_mul_f32_e32 v120, v120, v130
	v_mul_f32_e32 v121, v121, v130
	v_mul_f32_e32 v117, v117, v130
	v_mul_f32_e32 v122, v122, v130
	v_mul_f32_e32 v123, v123, v130
	v_mul_f32_e32 v124, v124, v130
	v_mul_f32_e32 v101, v101, v137
	v_mul_f32_e32 v118, v118, v130
	v_mul_f32_e32 v119, v119, v130
	v_mul_f32_e32 v145, v114, v130
	v_mul_f32_e32 v146, v115, v130
	v_mul_f32_e32 v147, v116, v130
	v_mul_f32_e32 v125, v125, v130
	v_cvt_pk_bf16_f32 v114, v118, v119
	v_cvt_pk_bf16_f32 v115, v120, v121
	v_cvt_pk_bf16_f32 v116, v145, v146
	v_cvt_pk_bf16_f32 v117, v147, v117
	v_cvt_pk_bf16_f32 v120, v122, v123
	v_cvt_pk_bf16_f32 v121, v124, v125
	v_mul_f32_e32 v102, v102, v137
	v_mul_f32_e32 v103, v103, v137
	v_mul_f32_e32 v104, v104, v137
	v_mul_f32_e32 v105, v105, v137
	v_mul_f32_e32 v122, v98, v137
	v_mul_f32_e32 v123, v99, v137
	v_mul_f32_e32 v124, v100, v137
	v_cvt_pk_bf16_f32 v98, v102, v103
	v_cvt_pk_bf16_f32 v99, v104, v105
	v_cvt_pk_bf16_f32 v100, v122, v123
	v_cvt_pk_bf16_f32 v101, v124, v101
	v_mul_f32_e32 v126, v126, v130
	v_mul_f32_e32 v127, v127, v130
	v_mul_f32_e32 v128, v128, v130
	v_mul_f32_e32 v129, v129, v130
	v_cvt_pk_bf16_f32 v118, v126, v127
	v_cvt_pk_bf16_f32 v119, v128, v129
	v_mul_f32_e32 v110, v110, v137
	v_mul_f32_e32 v111, v111, v137
	v_mul_f32_e32 v112, v112, v137
	v_mul_f32_e32 v113, v113, v137
	v_mul_f32_e32 v106, v106, v137
	v_mul_f32_e32 v107, v107, v137
	v_mul_f32_e32 v108, v108, v137
	v_mul_f32_e32 v109, v109, v137
	global_store_dwordx4 v[142:143], v[114:117], off
	global_store_dwordx4 v[142:143], v[118:121], off offset:256
	v_cvt_pk_bf16_f32 v102, v110, v111
	v_cvt_pk_bf16_f32 v103, v112, v113
	v_cvt_pk_bf16_f32 v104, v106, v107
	v_cvt_pk_bf16_f32 v105, v108, v109
	global_store_dwordx4 v[140:141], v[98:101], off
	global_store_dwordx4 v[140:141], v[102:105], off offset:256
	v_or_b32_e32 v98, 48, v136
	v_ashrrev_i32_e32 v99, 31, v98
	v_lshl_add_u64 v[100:101], v[98:99], 2, s[2:3]
	v_or_b32_e32 v99, 32, v136
	v_add_u32_e32 v100, 0x80, v136
	v_mad_i64_i32 v[102:103], s[22:23], v99, s36, v[132:133]
	v_mad_i64_i32 v[98:99], s[22:23], v98, s36, v[132:133]
	v_ashrrev_i32_e32 v101, 31, v100
	v_lshl_add_u64 v[102:103], v[102:103], 0, v[134:135]
	v_lshl_add_u64 v[98:99], v[98:99], 0, v[134:135]
	v_lshl_add_u64 v[104:105], v[100:101], 2, s[2:3]
	s_waitcnt vmcnt(8)
	v_mul_f32_e32 v78, v78, v150
	v_mul_f32_e32 v79, v79, v150
	v_mul_f32_e32 v80, v80, v150
	v_mul_f32_e32 v81, v81, v150
	v_mul_f32_e32 v74, v74, v150
	v_mul_f32_e32 v75, v75, v150
	v_mul_f32_e32 v76, v76, v150
	v_mul_f32_e32 v77, v77, v150
	s_waitcnt vmcnt(8)
	v_mul_f32_e32 v110, v66, v151
	v_mul_f32_e32 v111, v67, v151
	v_mul_f32_e32 v112, v68, v151
	v_mul_f32_e32 v113, v69, v151
	v_cvt_pk_bf16_f32 v66, v78, v79
	v_cvt_pk_bf16_f32 v67, v80, v81
	v_cvt_pk_bf16_f32 v68, v74, v75
	v_cvt_pk_bf16_f32 v69, v76, v77
	v_mul_f32_e32 v94, v94, v150
	v_mul_f32_e32 v95, v95, v150
	v_mul_f32_e32 v96, v96, v150
	v_mul_f32_e32 v97, v97, v150
	v_mul_f32_e32 v90, v90, v150
	v_mul_f32_e32 v91, v91, v150
	v_mul_f32_e32 v92, v92, v150
	v_mul_f32_e32 v93, v93, v150
	v_mul_f32_e32 v101, v70, v151
	v_mul_f32_e32 v106, v71, v151
	v_mul_f32_e32 v108, v72, v151
	v_mul_f32_e32 v109, v73, v151
	v_mul_f32_e32 v86, v86, v151
	v_mul_f32_e32 v87, v87, v151
	v_mul_f32_e32 v88, v88, v151
	v_mul_f32_e32 v89, v89, v151
	v_mul_f32_e32 v82, v82, v151
	v_mul_f32_e32 v83, v83, v151
	v_mul_f32_e32 v84, v84, v151
	v_mul_f32_e32 v85, v85, v151
	v_cvt_pk_bf16_f32 v70, v94, v95
	v_cvt_pk_bf16_f32 v71, v96, v97
	v_cvt_pk_bf16_f32 v72, v90, v91
	v_cvt_pk_bf16_f32 v73, v92, v93
	v_cvt_pk_bf16_f32 v74, v101, v106
	v_cvt_pk_bf16_f32 v75, v108, v109
	v_cvt_pk_bf16_f32 v76, v110, v111
	v_cvt_pk_bf16_f32 v77, v112, v113
	v_cvt_pk_bf16_f32 v78, v86, v87
	v_cvt_pk_bf16_f32 v79, v88, v89
	v_cvt_pk_bf16_f32 v80, v82, v83
	v_cvt_pk_bf16_f32 v81, v84, v85
	global_store_dwordx4 v[102:103], v[66:69], off
	global_store_dwordx4 v[102:103], v[70:73], off offset:256
	global_store_dwordx4 v[98:99], v[74:77], off
	global_store_dwordx4 v[98:99], v[78:81], off offset:256
	v_add_u32_e32 v66, 0x90, v136
	v_ashrrev_i32_e32 v67, 31, v66
	v_lshl_add_u64 v[68:69], v[66:67], 2, s[2:3]
	v_add_u32_e32 v68, 0xa0, v136
	v_mad_i64_i32 v[70:71], s[22:23], v100, s36, v[132:133]
	v_mad_i64_i32 v[66:67], s[22:23], v66, s36, v[132:133]
	v_ashrrev_i32_e32 v69, 31, v68
	v_lshl_add_u64 v[70:71], v[70:71], 0, v[134:135]
	v_lshl_add_u64 v[66:67], v[66:67], 0, v[134:135]
	v_lshl_add_u64 v[72:73], v[68:69], 2, s[2:3]
	s_waitcnt vmcnt(10)
	v_mul_f32_e32 v54, v54, v152
	v_mul_f32_e32 v55, v55, v152
	v_mul_f32_e32 v56, v56, v152
	v_mul_f32_e32 v57, v57, v152
	v_mul_f32_e32 v46, v46, v152
	v_mul_f32_e32 v47, v47, v152
	v_mul_f32_e32 v48, v48, v152
	v_mul_f32_e32 v49, v49, v152
	s_waitcnt vmcnt(10)
	v_mul_f32_e32 v78, v34, v153
	v_mul_f32_e32 v79, v35, v153
	v_mul_f32_e32 v80, v36, v153
	v_mul_f32_e32 v81, v37, v153
	v_cvt_pk_bf16_f32 v34, v54, v55
	v_cvt_pk_bf16_f32 v35, v56, v57
	v_cvt_pk_bf16_f32 v36, v46, v47
	v_cvt_pk_bf16_f32 v37, v48, v49
	v_mul_f32_e32 v62, v62, v152
	v_mul_f32_e32 v63, v63, v152
	v_mul_f32_e32 v64, v64, v152
	v_mul_f32_e32 v65, v65, v152
	v_mul_f32_e32 v58, v58, v152
	v_mul_f32_e32 v59, v59, v152
	v_mul_f32_e32 v60, v60, v152
	v_mul_f32_e32 v61, v61, v152
	v_mul_f32_e32 v69, v38, v153
	v_mul_f32_e32 v74, v39, v153
	v_mul_f32_e32 v76, v40, v153
	v_mul_f32_e32 v77, v41, v153
	v_mul_f32_e32 v50, v50, v153
	v_mul_f32_e32 v51, v51, v153
	v_mul_f32_e32 v52, v52, v153
	v_mul_f32_e32 v53, v53, v153
	v_mul_f32_e32 v82, v42, v153
	v_mul_f32_e32 v83, v43, v153
	v_mul_f32_e32 v84, v44, v153
	v_mul_f32_e32 v75, v45, v153
	v_cvt_pk_bf16_f32 v38, v62, v63
	v_cvt_pk_bf16_f32 v39, v64, v65
	v_cvt_pk_bf16_f32 v40, v58, v59
	v_cvt_pk_bf16_f32 v41, v60, v61
	v_cvt_pk_bf16_f32 v42, v69, v74
	v_cvt_pk_bf16_f32 v43, v76, v77
	v_cvt_pk_bf16_f32 v44, v78, v79
	v_cvt_pk_bf16_f32 v45, v80, v81
	v_cvt_pk_bf16_f32 v46, v50, v51
	v_cvt_pk_bf16_f32 v47, v52, v53
	v_cvt_pk_bf16_f32 v48, v82, v83
	v_cvt_pk_bf16_f32 v49, v84, v75
	global_store_dwordx4 v[70:71], v[34:37], off
	global_store_dwordx4 v[70:71], v[38:41], off offset:256
	global_store_dwordx4 v[66:67], v[42:45], off
	global_store_dwordx4 v[66:67], v[46:49], off offset:256
	v_add_u32_e32 v34, 0xb0, v136
	v_ashrrev_i32_e32 v35, 31, v34
	v_lshl_add_u64 v[36:37], v[34:35], 2, s[2:3]
	v_mad_i64_i32 v[36:37], s[22:23], v68, s36, v[132:133]
	v_mad_i64_i32 v[34:35], s[22:23], v34, s36, v[132:133]
	v_lshl_add_u64 v[36:37], v[36:37], 0, v[134:135]
	v_lshl_add_u64 v[34:35], v[34:35], 0, v[134:135]
	s_waitcnt vmcnt(12)
	v_mul_f32_e32 v22, v22, v154
	v_mul_f32_e32 v23, v23, v154
	v_mul_f32_e32 v24, v24, v154
	v_mul_f32_e32 v25, v25, v154
	v_mul_f32_e32 v14, v14, v154
	v_mul_f32_e32 v15, v15, v154
	v_mul_f32_e32 v16, v16, v154
	v_mul_f32_e32 v17, v17, v154
	s_waitcnt vmcnt(12)
	v_mul_f32_e32 v43, v2, v155
	v_mul_f32_e32 v44, v3, v155
	v_mul_f32_e32 v45, v4, v155
	v_mul_f32_e32 v46, v5, v155
	v_cvt_pk_bf16_f32 v2, v22, v23
	v_cvt_pk_bf16_f32 v3, v24, v25
	v_cvt_pk_bf16_f32 v4, v14, v15
	v_cvt_pk_bf16_f32 v5, v16, v17
	v_mul_f32_e32 v30, v30, v154
	v_mul_f32_e32 v31, v31, v154
	v_mul_f32_e32 v32, v32, v154
	v_mul_f32_e32 v33, v33, v154
	v_mul_f32_e32 v26, v26, v154
	v_mul_f32_e32 v27, v27, v154
	v_mul_f32_e32 v28, v28, v154
	v_mul_f32_e32 v29, v29, v154
	v_mul_f32_e32 v38, v6, v155
	v_mul_f32_e32 v40, v7, v155
	v_mul_f32_e32 v41, v8, v155
	v_mul_f32_e32 v42, v9, v155
	v_mul_f32_e32 v18, v18, v155
	v_mul_f32_e32 v19, v19, v155
	v_mul_f32_e32 v20, v20, v155
	v_mul_f32_e32 v21, v21, v155
	v_mul_f32_e32 v47, v10, v155
	v_mul_f32_e32 v48, v11, v155
	v_mul_f32_e32 v49, v12, v155
	v_mul_f32_e32 v39, v13, v155
	v_cvt_pk_bf16_f32 v6, v30, v31
	v_cvt_pk_bf16_f32 v7, v32, v33
	v_cvt_pk_bf16_f32 v8, v26, v27
	v_cvt_pk_bf16_f32 v9, v28, v29
	v_cvt_pk_bf16_f32 v10, v38, v40
	v_cvt_pk_bf16_f32 v11, v41, v42
	v_cvt_pk_bf16_f32 v12, v43, v44
	v_cvt_pk_bf16_f32 v13, v45, v46
	v_cvt_pk_bf16_f32 v14, v18, v19
	v_cvt_pk_bf16_f32 v15, v20, v21
	v_cvt_pk_bf16_f32 v16, v47, v48
	v_cvt_pk_bf16_f32 v17, v49, v39
	global_store_dwordx4 v[36:37], v[2:5], off
	global_store_dwordx4 v[36:37], v[6:9], off offset:256
	global_store_dwordx4 v[34:35], v[10:13], off
	global_store_dwordx4 v[34:35], v[14:17], off offset:256
	s_barrier
	s_cbranch_scc1 .LBB0_120
